# v31: v26 + GEMM re-alignment barrier of the second wave group moved below the next tile's header code and accumulator zeroing (that VALU no longer runs beside the partner's prioritised MFMA phase)
# speedup vs baseline: 1.0017x; 1.0017x over previous
.LBB0_308:
	s_ashr_i32 s19, s18, 31
	s_lshl_b64 s[26:27], s[18:19], 18
	s_add_u32 s42, s38, s26
	s_addc_u32 s43, s39, s27
	s_and_b64 s[26:27], s[40:41], exec
	s_cselect_b32 s19, s43, s49
	s_cselect_b32 s63, s42, s48
	s_ashr_i32 s17, s16, 31
	s_lshl_b64 s[26:27], s[16:17], 19
	s_add_u32 s44, s54, s26
	s_addc_u32 s45, s55, s27
	s_and_b64 s[26:27], s[40:41], exec
	s_cselect_b32 s17, s45, s51
	s_cselect_b32 s64, s44, s50
	s_add_u32 s48, s48, 0x40080
	s_addc_u32 s49, s49, 0
	s_add_u32 s65, s50, 0x100
	v_mov_b32_e32 v0, 0
	s_addc_u32 s66, s51, 0
	s_mov_b32 s67, -2
	v_mov_b32_e32 v1, v0
	v_mov_b32_e32 v2, v0
	v_mov_b32_e32 v3, v0
	v_mov_b32_e32 v4, v0
	v_mov_b32_e32 v5, v0
	v_mov_b32_e32 v6, v0
	v_mov_b32_e32 v7, v0
	v_mov_b32_e32 v16, v0
	v_mov_b32_e32 v17, v0
	v_mov_b32_e32 v18, v0
	v_mov_b32_e32 v19, v0
	v_mov_b32_e32 v20, v0
	v_mov_b32_e32 v21, v0
	v_mov_b32_e32 v22, v0
	v_mov_b32_e32 v23, v0
	v_mov_b32_e32 v32, v0
	v_mov_b32_e32 v33, v0
	v_mov_b32_e32 v34, v0
	v_mov_b32_e32 v35, v0
	v_mov_b32_e32 v36, v0
	v_mov_b32_e32 v37, v0
	v_mov_b32_e32 v38, v0
	v_mov_b32_e32 v39, v0
	v_mov_b32_e32 v48, v0
	v_mov_b32_e32 v49, v0
	v_mov_b32_e32 v50, v0
	v_mov_b32_e32 v51, v0
	v_mov_b32_e32 v52, v0
	v_mov_b32_e32 v53, v0
	v_mov_b32_e32 v54, v0
	v_mov_b32_e32 v55, v0
	v_mov_b32_e32 v8, v0
	v_mov_b32_e32 v9, v0
	v_mov_b32_e32 v10, v0
	v_mov_b32_e32 v11, v0
	v_mov_b32_e32 v12, v0
	v_mov_b32_e32 v13, v0
	v_mov_b32_e32 v14, v0
	v_mov_b32_e32 v15, v0
	v_mov_b32_e32 v24, v0
	v_mov_b32_e32 v25, v0
	v_mov_b32_e32 v26, v0
	v_mov_b32_e32 v27, v0
	v_mov_b32_e32 v28, v0
	v_mov_b32_e32 v29, v0
	v_mov_b32_e32 v30, v0
	v_mov_b32_e32 v31, v0
	v_mov_b32_e32 v40, v0
	v_mov_b32_e32 v41, v0
	v_mov_b32_e32 v42, v0
	v_mov_b32_e32 v43, v0
	v_mov_b32_e32 v44, v0
	v_mov_b32_e32 v45, v0
	v_mov_b32_e32 v46, v0
	v_mov_b32_e32 v47, v0
	v_mov_b32_e32 v64, v0
	v_mov_b32_e32 v65, v0
	v_mov_b32_e32 v66, v0
	v_mov_b32_e32 v67, v0
	v_mov_b32_e32 v76, v0
	v_mov_b32_e32 v77, v0
	v_mov_b32_e32 v78, v0
	v_mov_b32_e32 v79, v0
	v_mov_b32_e32 v80, v0
	v_mov_b32_e32 v81, v0
	v_mov_b32_e32 v82, v0
	v_mov_b32_e32 v83, v0
	v_mov_b32_e32 v84, v0
	v_mov_b32_e32 v85, v0
	v_mov_b32_e32 v86, v0
	v_mov_b32_e32 v87, v0
	v_mov_b32_e32 v98, v0
	v_mov_b32_e32 v99, v0
	v_mov_b32_e32 v100, v0
	v_mov_b32_e32 v101, v0
	v_mov_b32_e32 v102, v0
	v_mov_b32_e32 v103, v0
	v_mov_b32_e32 v104, v0
	v_mov_b32_e32 v105, v0
	v_mov_b32_e32 v114, v0
	v_mov_b32_e32 v115, v0
	v_mov_b32_e32 v116, v0
	v_mov_b32_e32 v117, v0
	v_mov_b32_e32 v118, v0
	v_mov_b32_e32 v119, v0
	v_mov_b32_e32 v120, v0
	v_mov_b32_e32 v121, v0
	v_mov_b32_e32 v130, v0
	v_mov_b32_e32 v131, v0
	v_mov_b32_e32 v132, v0
	v_mov_b32_e32 v133, v0
	v_mov_b32_e32 v134, v0
	v_mov_b32_e32 v135, v0
	v_mov_b32_e32 v136, v0
	v_mov_b32_e32 v137, v0
	v_mov_b32_e32 v88, v0
	v_mov_b32_e32 v89, v0
	v_mov_b32_e32 v90, v0
	v_mov_b32_e32 v91, v0
	v_mov_b32_e32 v92, v0
	v_mov_b32_e32 v93, v0
	v_mov_b32_e32 v94, v0
	v_mov_b32_e32 v95, v0
	v_mov_b32_e32 v106, v0
	v_mov_b32_e32 v107, v0
	v_mov_b32_e32 v108, v0
	v_mov_b32_e32 v109, v0
	v_mov_b32_e32 v110, v0
	v_mov_b32_e32 v111, v0
	v_mov_b32_e32 v112, v0
	v_mov_b32_e32 v113, v0
	v_mov_b32_e32 v122, v0
	v_mov_b32_e32 v123, v0
	v_mov_b32_e32 v124, v0
	v_mov_b32_e32 v125, v0
	v_mov_b32_e32 v126, v0
	v_mov_b32_e32 v127, v0
	v_mov_b32_e32 v128, v0
	v_mov_b32_e32 v129, v0
	v_mov_b32_e32 v138, v0
	v_mov_b32_e32 v139, v0
	v_mov_b32_e32 v140, v0
	v_mov_b32_e32 v141, v0
	v_mov_b32_e32 v142, v0
	v_mov_b32_e32 v143, v0
	v_mov_b32_e32 v144, v0
	v_mov_b32_e32 v145, v0
	v_add_u32_e32 v224, 0x10000, v167
	v_add_u32_e32 v225, 0x14000, v167
	v_add_u32_e32 v226, 0x18000, v167
	v_add_u32_e32 v227, 0x1c000, v167
	s_cmp_eq_u32 s62, 1
	s_cbranch_scc1 .Lrebar_0
	s_andn2_b64 vcc, exec, s[6:7]
	s_cbranch_vccnz .Lrebar_0
	s_barrier
.Lrebar_0:
.LBB0_309:
	s_add_u32 s26, s48, 0xfffc0080
	s_addc_u32 s27, s49, -1
	s_add_i32 s68, 0, 0x10000
	s_cmp_eq_u32 s67, 12
	s_cselect_b32 s53, s19, s27
	s_cselect_b32 s52, s63, s26
	s_cselect_b32 s51, s17, s66
	s_cselect_b32 s50, s64, s65
	s_add_i32 s69, 0, 0x14000
	ds_read_b128 v[56:59], v224
	ds_read_b128 v[60:63], v224 offset:1024
	ds_read_b128 v[68:71], v224 offset:2048
	ds_read_b128 v[72:75], v224 offset:3072
	ds_read_b128 v[158:161], v225
	ds_read_b128 v[162:165], v225 offset:1024
	ds_read_b128 v[170:173], v225 offset:2048
	ds_read_b128 v[174:177], v225 offset:3072
	s_add_i32 m0, s35, 0xc000
	ds_read_b128 v[178:181], v169
	ds_read_b128 v[182:185], v169 offset:1024
	ds_read_b128 v[186:189], v169 offset:2048
	ds_read_b128 v[190:193], v169 offset:3072
	ds_read_b128 v[198:201], v169 offset:4096
	ds_read_b128 v[202:205], v169 offset:5120
	ds_read_b128 v[206:209], v169 offset:6144
	ds_read_b128 v[210:213], v169 offset:7168
	global_load_lds_dwordx4 v154, s[48:49]
	s_add_i32 m0, s35, 0xe000
	s_nop 0
	global_load_lds_dwordx4 v156, s[48:49]
	s_waitcnt vmcnt(8)
	s_waitcnt lgkmcnt(0)
	s_barrier
	s_setprio 1
	s_waitcnt lgkmcnt(0)
	v_mfma_i32_16x16x64_i8 v[142:145], v[56:59], v[178:181], v[142:145]
	v_mfma_i32_16x16x64_i8 v[138:141], v[68:71], v[178:181], v[138:141]
	v_mfma_i32_16x16x64_i8 v[126:129], v[56:59], v[186:189], v[126:129]
	v_mfma_i32_16x16x64_i8 v[122:125], v[68:71], v[186:189], v[122:125]
	v_mfma_i32_16x16x64_i8 v[110:113], v[56:59], v[198:201], v[110:113]
	v_mfma_i32_16x16x64_i8 v[106:109], v[68:71], v[198:201], v[106:109]
	v_mfma_i32_16x16x64_i8 v[92:95], v[56:59], v[206:209], v[92:95]
	v_mfma_i32_16x16x64_i8 v[88:91], v[68:71], v[206:209], v[88:91]
	v_mfma_i32_16x16x64_i8 v[142:145], v[60:63], v[182:185], v[142:145]
	v_mfma_i32_16x16x64_i8 v[138:141], v[72:75], v[182:185], v[138:141]
	v_mfma_i32_16x16x64_i8 v[126:129], v[60:63], v[190:193], v[126:129]
	v_mfma_i32_16x16x64_i8 v[122:125], v[72:75], v[190:193], v[122:125]
	v_mfma_i32_16x16x64_i8 v[110:113], v[60:63], v[202:205], v[110:113]
	v_mfma_i32_16x16x64_i8 v[106:109], v[72:75], v[202:205], v[106:109]
	v_mfma_i32_16x16x64_i8 v[92:95], v[60:63], v[210:213], v[92:95]
	v_mfma_i32_16x16x64_i8 v[88:91], v[72:75], v[210:213], v[88:91]
	s_setprio 0
	s_setprio 1
	v_mfma_i32_16x16x64_i8 v[134:137], v[158:161], v[178:181], v[134:137]
	v_mfma_i32_16x16x64_i8 v[130:133], v[170:173], v[178:181], v[130:133]
	v_mfma_i32_16x16x64_i8 v[118:121], v[158:161], v[186:189], v[118:121]
	v_mfma_i32_16x16x64_i8 v[114:117], v[170:173], v[186:189], v[114:117]
	v_mfma_i32_16x16x64_i8 v[102:105], v[158:161], v[198:201], v[102:105]
	v_mfma_i32_16x16x64_i8 v[98:101], v[170:173], v[198:201], v[98:101]
	v_mfma_i32_16x16x64_i8 v[84:87], v[158:161], v[206:209], v[84:87]
	v_mfma_i32_16x16x64_i8 v[80:83], v[170:173], v[206:209], v[80:83]
	v_mfma_i32_16x16x64_i8 v[134:137], v[162:165], v[182:185], v[134:137]
	v_mfma_i32_16x16x64_i8 v[130:133], v[174:177], v[182:185], v[130:133]
	v_mfma_i32_16x16x64_i8 v[118:121], v[162:165], v[190:193], v[118:121]
	v_mfma_i32_16x16x64_i8 v[114:117], v[174:177], v[190:193], v[114:117]
	v_mfma_i32_16x16x64_i8 v[102:105], v[162:165], v[202:205], v[102:105]
	v_mfma_i32_16x16x64_i8 v[98:101], v[174:177], v[202:205], v[98:101]
	v_mfma_i32_16x16x64_i8 v[84:87], v[162:165], v[210:213], v[84:87]
	v_mfma_i32_16x16x64_i8 v[80:83], v[174:177], v[210:213], v[80:83]
	s_setprio 0
	s_barrier
	s_add_i32 s26, s68, s56
	s_mov_b32 m0, s26
	ds_read_b128 v[178:181], v169 offset:16384
	ds_read_b128 v[182:185], v169 offset:17408
	ds_read_b128 v[186:189], v169 offset:18432
	ds_read_b128 v[190:193], v169 offset:19456
	ds_read_b128 v[198:201], v169 offset:20480
	ds_read_b128 v[202:205], v169 offset:21504
	ds_read_b128 v[206:209], v169 offset:22528
	ds_read_b128 v[210:213], v169 offset:23552
	global_load_lds_dwordx4 v150, s[50:51]
	s_add_i32 m0, s26, 0x2000
	s_add_u32 s26, s50, 0x40000
	s_addc_u32 s27, s51, 0
	s_add_i32 s68, s69, s56
	global_load_lds_dwordx4 v146, s[50:51]
	s_mov_b32 m0, s68
	s_nop 0
	global_load_lds_dwordx4 v150, s[26:27]
	s_add_i32 m0, s68, 0x2000
	s_nop 0
	global_load_lds_dwordx4 v146, s[26:27]
	s_mov_b32 m0, s35
	s_nop 0
	global_load_lds_dwordx4 v152, s[52:53]
	s_mov_b32 m0, s57
	s_nop 0
	global_load_lds_dwordx4 v148, s[52:53]
	s_waitcnt vmcnt(8)
	s_waitcnt lgkmcnt(0)
	s_barrier
	s_setprio 1
	s_waitcnt lgkmcnt(0)
	v_mfma_i32_16x16x64_i8 v[76:79], v[56:59], v[178:181], v[76:79]
	v_mfma_i32_16x16x64_i8 v[64:67], v[68:71], v[178:181], v[64:67]
	v_mfma_i32_16x16x64_i8 v[44:47], v[56:59], v[186:189], v[44:47]
	v_mfma_i32_16x16x64_i8 v[40:43], v[68:71], v[186:189], v[40:43]
	v_mfma_i32_16x16x64_i8 v[28:31], v[56:59], v[198:201], v[28:31]
	v_mfma_i32_16x16x64_i8 v[24:27], v[68:71], v[198:201], v[24:27]
	v_mfma_i32_16x16x64_i8 v[12:15], v[56:59], v[206:209], v[12:15]
	v_mfma_i32_16x16x64_i8 v[8:11], v[68:71], v[206:209], v[8:11]
	v_mfma_i32_16x16x64_i8 v[76:79], v[60:63], v[182:185], v[76:79]
	v_mfma_i32_16x16x64_i8 v[64:67], v[72:75], v[182:185], v[64:67]
	v_mfma_i32_16x16x64_i8 v[44:47], v[60:63], v[190:193], v[44:47]
	v_mfma_i32_16x16x64_i8 v[40:43], v[72:75], v[190:193], v[40:43]
	v_mfma_i32_16x16x64_i8 v[28:31], v[60:63], v[202:205], v[28:31]
	v_mfma_i32_16x16x64_i8 v[24:27], v[72:75], v[202:205], v[24:27]
	v_mfma_i32_16x16x64_i8 v[12:15], v[60:63], v[210:213], v[12:15]
	v_mfma_i32_16x16x64_i8 v[8:11], v[72:75], v[210:213], v[8:11]
	s_setprio 0
	s_setprio 1
	v_mfma_i32_16x16x64_i8 v[52:55], v[158:161], v[178:181], v[52:55]
	v_mfma_i32_16x16x64_i8 v[48:51], v[170:173], v[178:181], v[48:51]
	v_mfma_i32_16x16x64_i8 v[36:39], v[158:161], v[186:189], v[36:39]
	v_mfma_i32_16x16x64_i8 v[32:35], v[170:173], v[186:189], v[32:35]
	v_mfma_i32_16x16x64_i8 v[20:23], v[158:161], v[198:201], v[20:23]
	v_mfma_i32_16x16x64_i8 v[16:19], v[170:173], v[198:201], v[16:19]
	v_mfma_i32_16x16x64_i8 v[4:7], v[158:161], v[206:209], v[4:7]
	v_mfma_i32_16x16x64_i8 v[0:3], v[170:173], v[206:209], v[0:3]
	v_mfma_i32_16x16x64_i8 v[52:55], v[162:165], v[182:185], v[52:55]
	v_mfma_i32_16x16x64_i8 v[48:51], v[174:177], v[182:185], v[48:51]
	v_mfma_i32_16x16x64_i8 v[36:39], v[162:165], v[190:193], v[36:39]
	v_mfma_i32_16x16x64_i8 v[32:35], v[174:177], v[190:193], v[32:35]
	v_mfma_i32_16x16x64_i8 v[20:23], v[162:165], v[202:205], v[20:23]
	v_mfma_i32_16x16x64_i8 v[16:19], v[174:177], v[202:205], v[16:19]
	v_mfma_i32_16x16x64_i8 v[4:7], v[162:165], v[210:213], v[4:7]
	v_mfma_i32_16x16x64_i8 v[0:3], v[174:177], v[210:213], v[0:3]
	s_setprio 0
	s_barrier
	s_add_i32 s68, 0, 0x18000
	s_add_i32 s69, 0, 0x1c000
	ds_read_b128 v[56:59], v226
	ds_read_b128 v[60:63], v226 offset:1024
	ds_read_b128 v[68:71], v226 offset:2048
	ds_read_b128 v[72:75], v226 offset:3072
	ds_read_b128 v[158:161], v227
	ds_read_b128 v[162:165], v227 offset:1024
	ds_read_b128 v[170:173], v227 offset:2048
	ds_read_b128 v[174:177], v227 offset:3072
	s_add_u32 s26, s52, 0x40000
	s_addc_u32 s27, s53, 0
	s_mov_b32 m0, s58
	ds_read_b128 v[178:181], v169 offset:32768
	ds_read_b128 v[182:185], v169 offset:33792
	ds_read_b128 v[186:189], v169 offset:34816
	ds_read_b128 v[190:193], v169 offset:35840
	ds_read_b128 v[198:201], v169 offset:36864
	ds_read_b128 v[202:205], v169 offset:37888
	ds_read_b128 v[206:209], v169 offset:38912
	ds_read_b128 v[210:213], v169 offset:39936
	global_load_lds_dwordx4 v152, s[26:27]
	s_mov_b32 m0, s59
	s_nop 0
	global_load_lds_dwordx4 v148, s[26:27]
	s_waitcnt vmcnt(8)
	s_waitcnt lgkmcnt(0)
	s_barrier
	s_setprio 1
	s_waitcnt lgkmcnt(0)
	v_mfma_i32_16x16x64_i8 v[142:145], v[56:59], v[178:181], v[142:145]
	v_mfma_i32_16x16x64_i8 v[138:141], v[68:71], v[178:181], v[138:141]
	v_mfma_i32_16x16x64_i8 v[126:129], v[56:59], v[186:189], v[126:129]
	v_mfma_i32_16x16x64_i8 v[122:125], v[68:71], v[186:189], v[122:125]
	v_mfma_i32_16x16x64_i8 v[110:113], v[56:59], v[198:201], v[110:113]
	v_mfma_i32_16x16x64_i8 v[106:109], v[68:71], v[198:201], v[106:109]
	v_mfma_i32_16x16x64_i8 v[92:95], v[56:59], v[206:209], v[92:95]
	v_mfma_i32_16x16x64_i8 v[88:91], v[68:71], v[206:209], v[88:91]
	v_mfma_i32_16x16x64_i8 v[142:145], v[60:63], v[182:185], v[142:145]
	v_mfma_i32_16x16x64_i8 v[138:141], v[72:75], v[182:185], v[138:141]
	v_mfma_i32_16x16x64_i8 v[126:129], v[60:63], v[190:193], v[126:129]
	v_mfma_i32_16x16x64_i8 v[122:125], v[72:75], v[190:193], v[122:125]
	v_mfma_i32_16x16x64_i8 v[110:113], v[60:63], v[202:205], v[110:113]
	v_mfma_i32_16x16x64_i8 v[106:109], v[72:75], v[202:205], v[106:109]
	v_mfma_i32_16x16x64_i8 v[92:95], v[60:63], v[210:213], v[92:95]
	v_mfma_i32_16x16x64_i8 v[88:91], v[72:75], v[210:213], v[88:91]
	s_setprio 0
	s_setprio 1
	v_mfma_i32_16x16x64_i8 v[134:137], v[158:161], v[178:181], v[134:137]
	v_mfma_i32_16x16x64_i8 v[130:133], v[170:173], v[178:181], v[130:133]
	v_mfma_i32_16x16x64_i8 v[118:121], v[158:161], v[186:189], v[118:121]
	v_mfma_i32_16x16x64_i8 v[114:117], v[170:173], v[186:189], v[114:117]
	v_mfma_i32_16x16x64_i8 v[102:105], v[158:161], v[198:201], v[102:105]
	v_mfma_i32_16x16x64_i8 v[98:101], v[170:173], v[198:201], v[98:101]
	v_mfma_i32_16x16x64_i8 v[84:87], v[158:161], v[206:209], v[84:87]
	v_mfma_i32_16x16x64_i8 v[80:83], v[170:173], v[206:209], v[80:83]
	v_mfma_i32_16x16x64_i8 v[134:137], v[162:165], v[182:185], v[134:137]
	v_mfma_i32_16x16x64_i8 v[130:133], v[174:177], v[182:185], v[130:133]
	v_mfma_i32_16x16x64_i8 v[118:121], v[162:165], v[190:193], v[118:121]
	v_mfma_i32_16x16x64_i8 v[114:117], v[174:177], v[190:193], v[114:117]
	v_mfma_i32_16x16x64_i8 v[102:105], v[162:165], v[202:205], v[102:105]
	v_mfma_i32_16x16x64_i8 v[98:101], v[174:177], v[202:205], v[98:101]
	v_mfma_i32_16x16x64_i8 v[84:87], v[162:165], v[210:213], v[84:87]
	v_mfma_i32_16x16x64_i8 v[80:83], v[174:177], v[210:213], v[80:83]
	s_setprio 0
	s_barrier
	s_add_i32 s26, s68, s56
	s_add_i32 m0, s26, 0xffffff80
	ds_read_b128 v[178:181], v169 offset:49152
	ds_read_b128 v[182:185], v169 offset:50176
	ds_read_b128 v[186:189], v169 offset:51200
	ds_read_b128 v[190:193], v169 offset:52224
	ds_read_b128 v[198:201], v169 offset:53248
	ds_read_b128 v[202:205], v169 offset:54272
	ds_read_b128 v[206:209], v169 offset:55296
	ds_read_b128 v[210:213], v169 offset:56320
	global_load_lds_dwordx4 v150, s[50:51] offset:128
	s_add_i32 m0, s26, 0x1f80
	s_add_u32 s26, s50, 0x40080
	s_addc_u32 s27, s51, 0
	s_add_i32 s100, s69, s56
	global_load_lds_dwordx4 v146, s[50:51] offset:128
	s_mov_b32 m0, s100
	s_nop 0
	global_load_lds_dwordx4 v150, s[26:27]
	s_add_i32 m0, s100, 0x2000
	s_nop 0
	global_load_lds_dwordx4 v146, s[26:27]
	s_add_i32 m0, s4, 0xffffff80
	s_nop 0
	global_load_lds_dwordx4 v152, s[52:53] offset:128
	s_add_i32 m0, s60, 0xffffff80
	s_nop 0
	global_load_lds_dwordx4 v148, s[52:53] offset:128
	s_waitcnt vmcnt(8)
	s_waitcnt lgkmcnt(0)
	s_barrier
	s_setprio 1
	s_waitcnt lgkmcnt(0)
	v_mfma_i32_16x16x64_i8 v[76:79], v[56:59], v[178:181], v[76:79]
	v_mfma_i32_16x16x64_i8 v[64:67], v[68:71], v[178:181], v[64:67]
	v_mfma_i32_16x16x64_i8 v[44:47], v[56:59], v[186:189], v[44:47]
	v_mfma_i32_16x16x64_i8 v[40:43], v[68:71], v[186:189], v[40:43]
	v_mfma_i32_16x16x64_i8 v[28:31], v[56:59], v[198:201], v[28:31]
	v_mfma_i32_16x16x64_i8 v[24:27], v[68:71], v[198:201], v[24:27]
	v_mfma_i32_16x16x64_i8 v[12:15], v[56:59], v[206:209], v[12:15]
	v_mfma_i32_16x16x64_i8 v[8:11], v[68:71], v[206:209], v[8:11]
	v_mfma_i32_16x16x64_i8 v[76:79], v[60:63], v[182:185], v[76:79]
	v_mfma_i32_16x16x64_i8 v[64:67], v[72:75], v[182:185], v[64:67]
	v_mfma_i32_16x16x64_i8 v[44:47], v[60:63], v[190:193], v[44:47]
	v_mfma_i32_16x16x64_i8 v[40:43], v[72:75], v[190:193], v[40:43]
	v_mfma_i32_16x16x64_i8 v[28:31], v[60:63], v[202:205], v[28:31]
	v_mfma_i32_16x16x64_i8 v[24:27], v[72:75], v[202:205], v[24:27]
	v_mfma_i32_16x16x64_i8 v[12:15], v[60:63], v[210:213], v[12:15]
	v_mfma_i32_16x16x64_i8 v[8:11], v[72:75], v[210:213], v[8:11]
	s_setprio 0
	s_setprio 1
	v_mfma_i32_16x16x64_i8 v[52:55], v[158:161], v[178:181], v[52:55]
	v_mfma_i32_16x16x64_i8 v[48:51], v[170:173], v[178:181], v[48:51]
	v_mfma_i32_16x16x64_i8 v[36:39], v[158:161], v[186:189], v[36:39]
	v_mfma_i32_16x16x64_i8 v[32:35], v[170:173], v[186:189], v[32:35]
	v_mfma_i32_16x16x64_i8 v[20:23], v[158:161], v[198:201], v[20:23]
	v_mfma_i32_16x16x64_i8 v[16:19], v[170:173], v[198:201], v[16:19]
	v_mfma_i32_16x16x64_i8 v[4:7], v[158:161], v[206:209], v[4:7]
	v_mfma_i32_16x16x64_i8 v[0:3], v[170:173], v[206:209], v[0:3]
	v_mfma_i32_16x16x64_i8 v[52:55], v[162:165], v[182:185], v[52:55]
	v_mfma_i32_16x16x64_i8 v[48:51], v[174:177], v[182:185], v[48:51]
	v_mfma_i32_16x16x64_i8 v[36:39], v[162:165], v[190:193], v[36:39]
	v_mfma_i32_16x16x64_i8 v[32:35], v[174:177], v[190:193], v[32:35]
	v_mfma_i32_16x16x64_i8 v[20:23], v[162:165], v[202:205], v[20:23]
	v_mfma_i32_16x16x64_i8 v[16:19], v[174:177], v[202:205], v[16:19]
	v_mfma_i32_16x16x64_i8 v[4:7], v[162:165], v[210:213], v[4:7]
	v_mfma_i32_16x16x64_i8 v[0:3], v[174:177], v[210:213], v[0:3]
	s_setprio 0
	s_barrier
	s_add_i32 s67, s67, 2
	s_add_u32 s48, s48, 0x100
	s_addc_u32 s49, s49, 0
	s_add_u32 s65, s65, 0x100
	s_addc_u32 s66, s66, 0
	s_cmp_gt_u32 s67, 13
	s_cbranch_scc0 .LBB0_309
	s_and_b64 vcc, exec, s[14:15]
	s_cbranch_vccz .LBB0_312
	s_barrier
.LBB0_312:
	v_lshl_or_b32 v160, s47, 8, v168
	v_lshl_add_u32 v162, s46, 7, v97
	v_ashrrev_i32_e32 v161, 31, v160
	v_ashrrev_i32_e32 v163, 31, v162
	v_lshl_add_u64 v[60:61], v[160:161], 2, s[12:13]
	v_lshl_add_u64 v[164:165], v[162:163], 2, s[10:11]
	global_load_dwordx4 v[68:71], v[60:61], off offset:16
	global_load_dwordx4 v[72:75], v[60:61], off
	global_load_dwordx4 v[56:59], v[60:61], off offset:528
	s_nop 0
	global_load_dwordx4 v[60:63], v[60:61], off offset:512
	v_cvt_f32_i32_e32 v143, v143
	global_load_dword v170, v[164:165], off
	global_load_dword v166, v[164:165], off offset:64
	v_cvt_f32_i32_e32 v142, v142
	v_cvt_f32_i32_e32 v145, v145
	v_cvt_f32_i32_e32 v144, v144
	v_cvt_f32_i32_e32 v139, v139
	v_cvt_f32_i32_e32 v138, v138
	v_cvt_f32_i32_e32 v141, v141
	v_cvt_f32_i32_e32 v140, v140
	v_mov_b64_e32 v[158:159], s[8:9]
	v_cvt_f32_i32_e32 v135, v135
	v_cvt_f32_i32_e32 v134, v134
	v_cvt_f32_i32_e32 v137, v137
	v_cvt_f32_i32_e32 v136, v136
	v_mad_i64_i32 v[172:173], s[26:27], v162, s21, v[158:159]
	v_lshlrev_b64 v[160:161], 1, v[160:161]
	v_cvt_f32_i32_e32 v131, v131
	v_cvt_f32_i32_e32 v130, v130
	v_cvt_f32_i32_e32 v133, v133
	v_cvt_f32_i32_e32 v132, v132
	v_lshl_add_u64 v[172:173], v[172:173], 0, v[160:161]
	v_cvt_f32_i32_e32 v127, v127
	v_cvt_f32_i32_e32 v126, v126
	v_cvt_f32_i32_e32 v129, v129
	v_cvt_f32_i32_e32 v128, v128
	v_cvt_f32_i32_e32 v123, v123
	v_cvt_f32_i32_e32 v122, v122
	v_cvt_f32_i32_e32 v125, v125
	v_cvt_f32_i32_e32 v124, v124
	v_cvt_f32_i32_e32 v119, v119
	v_cvt_f32_i32_e32 v118, v118
	v_cvt_f32_i32_e32 v121, v121
	v_cvt_f32_i32_e32 v120, v120
	v_cvt_f32_i32_e32 v115, v115
	v_cvt_f32_i32_e32 v114, v114
	v_cvt_f32_i32_e32 v117, v117
	v_cvt_f32_i32_e32 v116, v116
	v_cvt_f32_i32_e32 v111, v111
	v_cvt_f32_i32_e32 v110, v110
	v_cvt_f32_i32_e32 v113, v113
	v_cvt_f32_i32_e32 v112, v112
	v_cvt_f32_i32_e32 v107, v107
	v_cvt_f32_i32_e32 v106, v106
	v_cvt_f32_i32_e32 v109, v109
	v_cvt_f32_i32_e32 v108, v108
	v_cvt_f32_i32_e32 v103, v103
	v_cvt_f32_i32_e32 v102, v102
	v_cvt_f32_i32_e32 v105, v105
	v_cvt_f32_i32_e32 v104, v104
	v_cvt_f32_i32_e32 v99, v99
	v_cvt_f32_i32_e32 v98, v98
	v_cvt_f32_i32_e32 v101, v101
	v_cvt_f32_i32_e32 v100, v100
	v_cvt_f32_i32_e32 v93, v93
	v_cvt_f32_i32_e32 v92, v92
	v_cvt_f32_i32_e32 v95, v95
	v_cvt_f32_i32_e32 v94, v94
	v_cvt_f32_i32_e32 v89, v89
	v_cvt_f32_i32_e32 v88, v88
	v_cvt_f32_i32_e32 v91, v91
	v_cvt_f32_i32_e32 v90, v90
	v_cvt_f32_i32_e32 v85, v85
	v_cvt_f32_i32_e32 v84, v84
	v_cvt_f32_i32_e32 v87, v87
	v_cvt_f32_i32_e32 v86, v86
	v_cvt_f32_i32_e32 v81, v81
	v_cvt_f32_i32_e32 v80, v80
	v_cvt_f32_i32_e32 v83, v83
	v_cvt_f32_i32_e32 v82, v82
	v_cvt_f32_i32_e32 v77, v77
	v_cvt_f32_i32_e32 v76, v76
	v_cvt_f32_i32_e32 v79, v79
	v_cvt_f32_i32_e32 v78, v78
	v_cvt_f32_i32_e32 v65, v65
	v_cvt_f32_i32_e32 v64, v64
	v_cvt_f32_i32_e32 v67, v67
	v_cvt_f32_i32_e32 v66, v66
	v_cvt_f32_i32_e32 v53, v53
	v_cvt_f32_i32_e32 v52, v52
	s_waitcnt vmcnt(0)
	v_pk_mul_f32 v[174:175], v[72:73], v[170:171] op_sel_hi:[1,0]
	v_pk_mul_f32 v[176:177], v[74:75], v[170:171] op_sel_hi:[1,0]
	v_pk_mul_f32 v[142:143], v[174:175], v[142:143]
	v_pk_mul_f32 v[144:145], v[176:177], v[144:145]
	v_pk_mul_f32 v[174:175], v[68:69], v[170:171] op_sel_hi:[1,0]
	v_pk_mul_f32 v[176:177], v[70:71], v[170:171] op_sel_hi:[1,0]
	v_cvt_f32_i32_e32 v55, v55
	v_pk_mul_f32 v[176:177], v[176:177], v[140:141]
	v_pk_mul_f32 v[140:141], v[174:175], v[138:139]
	v_cvt_pk_bf16_f32 v138, v142, v143
	v_cvt_pk_bf16_f32 v139, v144, v145
	v_cvt_f32_i32_e32 v54, v54
	v_cvt_pk_bf16_f32 v140, v140, v141
	v_cvt_pk_bf16_f32 v141, v176, v177
	global_store_dwordx4 v[172:173], v[138:141], off
	v_cvt_f32_i32_e32 v49, v49
	v_cvt_f32_i32_e32 v48, v48
	v_pk_mul_f32 v[138:139], v[60:61], v[170:171] op_sel_hi:[1,0]
	v_pk_mul_f32 v[140:141], v[62:63], v[170:171] op_sel_hi:[1,0]
	v_pk_mul_f32 v[134:135], v[138:139], v[134:135]
	v_pk_mul_f32 v[136:137], v[140:141], v[136:137]
	v_pk_mul_f32 v[138:139], v[56:57], v[170:171] op_sel_hi:[1,0]
	v_pk_mul_f32 v[140:141], v[58:59], v[170:171] op_sel_hi:[1,0]
	v_cvt_f32_i32_e32 v51, v51
	v_pk_mul_f32 v[140:141], v[140:141], v[132:133]
	v_pk_mul_f32 v[132:133], v[138:139], v[130:131]
	v_cvt_pk_bf16_f32 v130, v134, v135
	v_cvt_pk_bf16_f32 v131, v136, v137
	v_pk_mul_f32 v[134:135], v[72:73], v[166:167] op_sel_hi:[1,0]
	v_cvt_pk_bf16_f32 v132, v132, v133
	v_cvt_pk_bf16_f32 v133, v140, v141
	global_store_dwordx4 v[172:173], v[130:133], off offset:256
	v_pk_mul_f32 v[136:137], v[74:75], v[166:167] op_sel_hi:[1,0]
	v_pk_mul_f32 v[126:127], v[134:135], v[126:127]
	v_or_b32_e32 v130, 16, v162
	v_mad_i64_i32 v[130:131], s[26:27], v130, s21, v[158:159]
	v_lshl_add_u64 v[132:133], v[130:131], 0, v[160:161]
	global_load_dword v130, v[164:165], off offset:128
	v_pk_mul_f32 v[128:129], v[136:137], v[128:129]
	v_pk_mul_f32 v[134:135], v[68:69], v[166:167] op_sel_hi:[1,0]
	v_pk_mul_f32 v[136:137], v[70:71], v[166:167] op_sel_hi:[1,0]
	v_cvt_f32_i32_e32 v50, v50
	v_pk_mul_f32 v[136:137], v[136:137], v[124:125]
	v_pk_mul_f32 v[124:125], v[134:135], v[122:123]
	v_cvt_pk_bf16_f32 v122, v126, v127
	v_cvt_pk_bf16_f32 v123, v128, v129
	v_cvt_f32_i32_e32 v45, v45
	v_cvt_pk_bf16_f32 v124, v124, v125
	v_cvt_pk_bf16_f32 v125, v136, v137
	global_store_dwordx4 v[132:133], v[122:125], off
	v_cvt_f32_i32_e32 v44, v44
	v_cvt_f32_i32_e32 v47, v47
	v_pk_mul_f32 v[122:123], v[60:61], v[166:167] op_sel_hi:[1,0]
	v_pk_mul_f32 v[124:125], v[62:63], v[166:167] op_sel_hi:[1,0]
	v_pk_mul_f32 v[118:119], v[122:123], v[118:119]
	v_pk_mul_f32 v[120:121], v[124:125], v[120:121]
	v_pk_mul_f32 v[122:123], v[56:57], v[166:167] op_sel_hi:[1,0]
	v_pk_mul_f32 v[124:125], v[58:59], v[166:167] op_sel_hi:[1,0]
	v_cvt_f32_i32_e32 v46, v46
	v_pk_mul_f32 v[124:125], v[124:125], v[116:117]
	v_pk_mul_f32 v[116:117], v[122:123], v[114:115]
	v_cvt_pk_bf16_f32 v114, v118, v119
	v_cvt_pk_bf16_f32 v115, v120, v121
	v_cvt_f32_i32_e32 v41, v41
	v_cvt_pk_bf16_f32 v116, v116, v117
	v_cvt_pk_bf16_f32 v117, v124, v125
	global_store_dwordx4 v[132:133], v[114:117], off offset:256
	v_cvt_f32_i32_e32 v40, v40
	v_cvt_f32_i32_e32 v43, v43
	v_or_b32_e32 v114, 32, v162
	v_mad_i64_i32 v[114:115], s[26:27], v114, s21, v[158:159]
	v_lshl_add_u64 v[116:117], v[114:115], 0, v[160:161]
	global_load_dword v114, v[164:165], off offset:192
	v_cvt_f32_i32_e32 v42, v42
	v_cvt_f32_i32_e32 v37, v37
	v_cvt_f32_i32_e32 v36, v36
	v_cvt_f32_i32_e32 v39, v39
	v_cvt_f32_i32_e32 v38, v38
	v_cvt_f32_i32_e32 v33, v33
	v_cvt_f32_i32_e32 v32, v32
	v_cvt_f32_i32_e32 v35, v35
	v_cvt_f32_i32_e32 v34, v34
	v_cvt_f32_i32_e32 v29, v29
	v_cvt_f32_i32_e32 v28, v28
	v_cvt_f32_i32_e32 v31, v31
	v_cvt_f32_i32_e32 v30, v30
	v_cvt_f32_i32_e32 v25, v25
	v_cvt_f32_i32_e32 v24, v24
	v_cvt_f32_i32_e32 v27, v27
	v_cvt_f32_i32_e32 v26, v26
	v_cvt_f32_i32_e32 v21, v21
	v_cvt_f32_i32_e32 v20, v20
	v_cvt_f32_i32_e32 v23, v23
	v_cvt_f32_i32_e32 v22, v22
	v_cvt_f32_i32_e32 v17, v17
	v_cvt_f32_i32_e32 v16, v16
	v_cvt_f32_i32_e32 v19, v19
	v_cvt_f32_i32_e32 v18, v18
	v_cvt_f32_i32_e32 v13, v13
	v_cvt_f32_i32_e32 v12, v12
	v_cvt_f32_i32_e32 v15, v15
	v_cvt_f32_i32_e32 v14, v14
	v_cvt_f32_i32_e32 v9, v9
	v_cvt_f32_i32_e32 v8, v8
	v_cvt_f32_i32_e32 v11, v11
	v_cvt_f32_i32_e32 v10, v10
	v_cvt_f32_i32_e32 v5, v5
	v_cvt_f32_i32_e32 v4, v4
	v_cvt_f32_i32_e32 v7, v7
	v_cvt_f32_i32_e32 v6, v6
	v_cvt_f32_i32_e32 v1, v1
	v_cvt_f32_i32_e32 v0, v0
	v_cvt_f32_i32_e32 v3, v3
	v_cvt_f32_i32_e32 v2, v2
	s_mov_b64 s[46:47], -1
	s_andn2_b64 vcc, exec, s[40:41]
	s_waitcnt vmcnt(3)
	v_pk_mul_f32 v[118:119], v[72:73], v[130:131] op_sel_hi:[1,0]
	v_pk_mul_f32 v[120:121], v[74:75], v[130:131] op_sel_hi:[1,0]
	v_pk_mul_f32 v[110:111], v[118:119], v[110:111]
	v_pk_mul_f32 v[112:113], v[120:121], v[112:113]
	v_pk_mul_f32 v[118:119], v[68:69], v[130:131] op_sel_hi:[1,0]
	v_pk_mul_f32 v[120:121], v[70:71], v[130:131] op_sel_hi:[1,0]
	s_mov_b64 s[68:69], 0x4000
	v_pk_mul_f32 v[120:121], v[120:121], v[108:109]
	v_pk_mul_f32 v[108:109], v[118:119], v[106:107]
	v_cvt_pk_bf16_f32 v106, v110, v111
	v_cvt_pk_bf16_f32 v107, v112, v113
	s_mov_b64 s[64:65], 0xfff
	v_cvt_pk_bf16_f32 v108, v108, v109
	v_cvt_pk_bf16_f32 v109, v120, v121
	global_store_dwordx4 v[116:117], v[106:109], off
	s_nop 1
	v_pk_mul_f32 v[106:107], v[60:61], v[130:131] op_sel_hi:[1,0]
	v_pk_mul_f32 v[108:109], v[62:63], v[130:131] op_sel_hi:[1,0]
	v_pk_mul_f32 v[102:103], v[106:107], v[102:103]
	v_pk_mul_f32 v[104:105], v[108:109], v[104:105]
	v_pk_mul_f32 v[106:107], v[56:57], v[130:131] op_sel_hi:[1,0]
	v_pk_mul_f32 v[108:109], v[58:59], v[130:131] op_sel_hi:[1,0]
	s_nop 0
	v_pk_mul_f32 v[108:109], v[108:109], v[100:101]
	v_pk_mul_f32 v[100:101], v[106:107], v[98:99]
	v_cvt_pk_bf16_f32 v98, v102, v103
	v_cvt_pk_bf16_f32 v99, v104, v105
	s_waitcnt vmcnt(1)
	v_pk_mul_f32 v[102:103], v[72:73], v[114:115] op_sel_hi:[1,0]
	v_cvt_pk_bf16_f32 v100, v100, v101
	v_cvt_pk_bf16_f32 v101, v108, v109
	global_store_dwordx4 v[116:117], v[98:101], off offset:256
	v_pk_mul_f32 v[104:105], v[74:75], v[114:115] op_sel_hi:[1,0]
	v_pk_mul_f32 v[92:93], v[102:103], v[92:93]
	v_or_b32_e32 v98, 48, v162
	v_mad_i64_i32 v[98:99], s[26:27], v98, s21, v[158:159]
	v_lshl_add_u64 v[100:101], v[98:99], 0, v[160:161]
	global_load_dword v98, v[164:165], off offset:512
	v_pk_mul_f32 v[94:95], v[104:105], v[94:95]
	v_pk_mul_f32 v[102:103], v[68:69], v[114:115] op_sel_hi:[1,0]
	v_pk_mul_f32 v[104:105], v[70:71], v[114:115] op_sel_hi:[1,0]
	s_nop 0
	v_pk_mul_f32 v[104:105], v[104:105], v[90:91]
	v_pk_mul_f32 v[90:91], v[102:103], v[88:89]
	v_cvt_pk_bf16_f32 v88, v92, v93
	v_cvt_pk_bf16_f32 v89, v94, v95
	s_nop 0
	v_cvt_pk_bf16_f32 v90, v90, v91
	v_cvt_pk_bf16_f32 v91, v104, v105
	global_store_dwordx4 v[100:101], v[88:91], off
	s_nop 1
	v_pk_mul_f32 v[88:89], v[60:61], v[114:115] op_sel_hi:[1,0]
	v_pk_mul_f32 v[90:91], v[62:63], v[114:115] op_sel_hi:[1,0]
	v_pk_mul_f32 v[84:85], v[88:89], v[84:85]
	v_pk_mul_f32 v[86:87], v[90:91], v[86:87]
	v_pk_mul_f32 v[88:89], v[56:57], v[114:115] op_sel_hi:[1,0]
	v_pk_mul_f32 v[90:91], v[58:59], v[114:115] op_sel_hi:[1,0]
	s_nop 0
	v_pk_mul_f32 v[90:91], v[90:91], v[82:83]
	v_pk_mul_f32 v[82:83], v[88:89], v[80:81]
	v_cvt_pk_bf16_f32 v80, v84, v85
	v_cvt_pk_bf16_f32 v81, v86, v87
	s_waitcnt vmcnt(1)
	v_pk_mul_f32 v[84:85], v[72:73], v[98:99] op_sel_hi:[1,0]
	v_cvt_pk_bf16_f32 v82, v82, v83
	v_cvt_pk_bf16_f32 v83, v90, v91
	global_store_dwordx4 v[100:101], v[80:83], off offset:256
	v_pk_mul_f32 v[86:87], v[74:75], v[98:99] op_sel_hi:[1,0]
	v_pk_mul_f32 v[76:77], v[84:85], v[76:77]
	v_add_u32_e32 v80, 0x80, v162
	v_mad_i64_i32 v[80:81], s[26:27], v80, s21, v[158:159]
	v_lshl_add_u64 v[82:83], v[80:81], 0, v[160:161]
	global_load_dword v80, v[164:165], off offset:576
	v_pk_mul_f32 v[78:79], v[86:87], v[78:79]
	v_pk_mul_f32 v[84:85], v[68:69], v[98:99] op_sel_hi:[1,0]
	v_pk_mul_f32 v[86:87], v[70:71], v[98:99] op_sel_hi:[1,0]
	s_nop 0
	v_pk_mul_f32 v[86:87], v[86:87], v[66:67]
	v_pk_mul_f32 v[66:67], v[84:85], v[64:65]
	v_cvt_pk_bf16_f32 v64, v76, v77
	v_cvt_pk_bf16_f32 v65, v78, v79
	s_nop 0
	v_cvt_pk_bf16_f32 v66, v66, v67
	v_cvt_pk_bf16_f32 v67, v86, v87
	global_store_dwordx4 v[82:83], v[64:67], off
	s_nop 1
	v_pk_mul_f32 v[64:65], v[60:61], v[98:99] op_sel_hi:[1,0]
	v_pk_mul_f32 v[66:67], v[62:63], v[98:99] op_sel_hi:[1,0]
	v_pk_mul_f32 v[52:53], v[64:65], v[52:53]
	v_pk_mul_f32 v[54:55], v[66:67], v[54:55]
	v_pk_mul_f32 v[64:65], v[56:57], v[98:99] op_sel_hi:[1,0]
	v_pk_mul_f32 v[66:67], v[58:59], v[98:99] op_sel_hi:[1,0]
	s_nop 0
	v_pk_mul_f32 v[66:67], v[66:67], v[50:51]
	v_pk_mul_f32 v[50:51], v[64:65], v[48:49]
	v_cvt_pk_bf16_f32 v48, v52, v53
	v_cvt_pk_bf16_f32 v49, v54, v55
	s_waitcnt vmcnt(1)
	v_pk_mul_f32 v[52:53], v[72:73], v[80:81] op_sel_hi:[1,0]
	v_cvt_pk_bf16_f32 v50, v50, v51
	v_cvt_pk_bf16_f32 v51, v66, v67
	global_store_dwordx4 v[82:83], v[48:51], off offset:256
	v_pk_mul_f32 v[54:55], v[74:75], v[80:81] op_sel_hi:[1,0]
	v_pk_mul_f32 v[44:45], v[52:53], v[44:45]
	v_add_u32_e32 v48, 0x90, v162
	v_mad_i64_i32 v[48:49], s[26:27], v48, s21, v[158:159]
	v_lshl_add_u64 v[50:51], v[48:49], 0, v[160:161]
	global_load_dword v48, v[164:165], off offset:640
	v_pk_mul_f32 v[46:47], v[54:55], v[46:47]
	v_pk_mul_f32 v[52:53], v[68:69], v[80:81] op_sel_hi:[1,0]
	v_pk_mul_f32 v[54:55], v[70:71], v[80:81] op_sel_hi:[1,0]
	s_nop 0
	v_pk_mul_f32 v[54:55], v[54:55], v[42:43]
	v_pk_mul_f32 v[42:43], v[52:53], v[40:41]
	v_cvt_pk_bf16_f32 v40, v44, v45
	v_cvt_pk_bf16_f32 v41, v46, v47
	s_nop 0
	v_cvt_pk_bf16_f32 v42, v42, v43
	v_cvt_pk_bf16_f32 v43, v54, v55
	global_store_dwordx4 v[50:51], v[40:43], off
	s_nop 1
	v_pk_mul_f32 v[40:41], v[60:61], v[80:81] op_sel_hi:[1,0]
	v_pk_mul_f32 v[42:43], v[62:63], v[80:81] op_sel_hi:[1,0]
	v_pk_mul_f32 v[36:37], v[40:41], v[36:37]
	v_pk_mul_f32 v[38:39], v[42:43], v[38:39]
	v_pk_mul_f32 v[40:41], v[56:57], v[80:81] op_sel_hi:[1,0]
	v_pk_mul_f32 v[42:43], v[58:59], v[80:81] op_sel_hi:[1,0]
	s_nop 0
	v_pk_mul_f32 v[42:43], v[42:43], v[34:35]
	v_pk_mul_f32 v[34:35], v[40:41], v[32:33]
	v_cvt_pk_bf16_f32 v32, v36, v37
	v_cvt_pk_bf16_f32 v33, v38, v39
	s_waitcnt vmcnt(1)
	v_pk_mul_f32 v[36:37], v[72:73], v[48:49] op_sel_hi:[1,0]
	v_cvt_pk_bf16_f32 v34, v34, v35
	v_cvt_pk_bf16_f32 v35, v42, v43
	global_store_dwordx4 v[50:51], v[32:35], off offset:256
	v_pk_mul_f32 v[38:39], v[74:75], v[48:49] op_sel_hi:[1,0]
	v_pk_mul_f32 v[28:29], v[36:37], v[28:29]
	v_add_u32_e32 v32, 0xa0, v162
	v_mad_i64_i32 v[32:33], s[26:27], v32, s21, v[158:159]
	v_lshl_add_u64 v[34:35], v[32:33], 0, v[160:161]
	global_load_dword v32, v[164:165], off offset:704
	v_pk_mul_f32 v[30:31], v[38:39], v[30:31]
	v_pk_mul_f32 v[36:37], v[68:69], v[48:49] op_sel_hi:[1,0]
	v_pk_mul_f32 v[38:39], v[70:71], v[48:49] op_sel_hi:[1,0]
	s_nop 0
	v_pk_mul_f32 v[38:39], v[38:39], v[26:27]
	v_pk_mul_f32 v[26:27], v[36:37], v[24:25]
	v_cvt_pk_bf16_f32 v24, v28, v29
	v_cvt_pk_bf16_f32 v25, v30, v31
	s_nop 0
	v_cvt_pk_bf16_f32 v26, v26, v27
	v_cvt_pk_bf16_f32 v27, v38, v39
	global_store_dwordx4 v[34:35], v[24:27], off
	s_nop 1
	v_pk_mul_f32 v[24:25], v[60:61], v[48:49] op_sel_hi:[1,0]
	v_pk_mul_f32 v[26:27], v[62:63], v[48:49] op_sel_hi:[1,0]
	v_pk_mul_f32 v[20:21], v[24:25], v[20:21]
	v_pk_mul_f32 v[22:23], v[26:27], v[22:23]
	v_pk_mul_f32 v[24:25], v[56:57], v[48:49] op_sel_hi:[1,0]
	v_pk_mul_f32 v[26:27], v[58:59], v[48:49] op_sel_hi:[1,0]
	s_nop 0
	v_pk_mul_f32 v[26:27], v[26:27], v[18:19]
	v_pk_mul_f32 v[18:19], v[24:25], v[16:17]
	v_cvt_pk_bf16_f32 v16, v20, v21
	v_cvt_pk_bf16_f32 v17, v22, v23
	s_waitcnt vmcnt(1)
	v_pk_mul_f32 v[20:21], v[74:75], v[32:33] op_sel_hi:[1,0]
	v_cvt_pk_bf16_f32 v18, v18, v19
	v_cvt_pk_bf16_f32 v19, v26, v27
	global_store_dwordx4 v[34:35], v[16:19], off offset:256
	v_pk_mul_f32 v[14:15], v[20:21], v[14:15]
	v_pk_mul_f32 v[20:21], v[70:71], v[32:33] op_sel_hi:[1,0]
	v_pk_mul_f32 v[18:19], v[72:73], v[32:33] op_sel_hi:[1,0]
	v_add_u32_e32 v16, 0xb0, v162
	v_pk_mul_f32 v[12:13], v[18:19], v[12:13]
	v_pk_mul_f32 v[18:19], v[68:69], v[32:33] op_sel_hi:[1,0]
	v_mad_i64_i32 v[16:17], s[26:27], v16, s21, v[158:159]
	v_pk_mul_f32 v[20:21], v[20:21], v[10:11]
	v_pk_mul_f32 v[10:11], v[18:19], v[8:9]
	v_lshl_add_u64 v[16:17], v[16:17], 0, v[160:161]
	v_cvt_pk_bf16_f32 v8, v12, v13
	v_cvt_pk_bf16_f32 v9, v14, v15
	v_cvt_pk_bf16_f32 v10, v10, v11
	v_cvt_pk_bf16_f32 v11, v20, v21
	global_store_dwordx4 v[16:17], v[8:11], off
	s_nop 1
	v_pk_mul_f32 v[8:9], v[60:61], v[32:33] op_sel_hi:[1,0]
	v_pk_mul_f32 v[10:11], v[62:63], v[32:33] op_sel_hi:[1,0]
	v_pk_mul_f32 v[4:5], v[8:9], v[4:5]
	v_pk_mul_f32 v[6:7], v[10:11], v[6:7]
	v_pk_mul_f32 v[8:9], v[56:57], v[32:33] op_sel_hi:[1,0]
	v_pk_mul_f32 v[10:11], v[58:59], v[32:33] op_sel_hi:[1,0]
	s_nop 0
	v_pk_mul_f32 v[10:11], v[10:11], v[2:3]
	v_pk_mul_f32 v[2:3], v[8:9], v[0:1]
	v_cvt_pk_bf16_f32 v0, v4, v5
	v_cvt_pk_bf16_f32 v1, v6, v7
	s_nop 0
	v_cvt_pk_bf16_f32 v2, v2, v3
	v_cvt_pk_bf16_f32 v3, v10, v11
	global_store_dwordx4 v[16:17], v[0:3], off offset:256
	s_cbranch_vccnz .LBB0_305
	s_andn2_b64 vcc, exec, s[6:7]
	s_cbranch_vccnz .LBB0_304
	s_branch .LBB0_304

.LBB0_687:
	s_cmp_eq_u32 s12, 2
	s_cselect_b32 s4, 0x4c0000, 0
	s_cmp_eq_u32 s69, 2
	s_cselect_b64 s[58:59], -1, 0
	s_ashr_i32 s45, s44, 31
	s_lshl_b64 s[6:7], s[44:45], 20
	s_add_u32 s48, s72, s6
	s_addc_u32 s49, s73, s7
	s_and_b64 s[6:7], s[56:57], exec
	s_cselect_b32 s34, s49, s43
	s_cselect_b32 s35, s48, s42
	s_add_u32 s6, s54, 0x80
	s_addc_u32 s7, s55, 0
	v_lshl_add_u64 v[0:1], s[6:7], 0, v[206:207]
	v_lshl_add_u64 v[210:211], v[0:1], 0, s[52:53]
	v_lshl_add_u64 v[0:1], s[6:7], 0, v[208:209]
	v_mov_b32_e32 v97, v96
	v_lshl_add_u64 v[212:213], v[0:1], 0, s[52:53]
	s_add_u32 s45, s42, 0x100
	v_mov_b32_e32 v98, v96
	v_mov_b32_e32 v99, v96
	v_mov_b32_e32 v64, 0
	v_mov_b64_e32 v[0:1], v[96:97]
	v_mov_b64_e32 v[4:5], v[96:97]
	v_mov_b64_e32 v[16:17], v[96:97]
	v_mov_b64_e32 v[20:21], v[96:97]
	v_mov_b64_e32 v[32:33], v[96:97]
	v_mov_b64_e32 v[36:37], v[96:97]
	v_mov_b64_e32 v[48:49], v[96:97]
	v_mov_b64_e32 v[52:53], v[96:97]
	v_mov_b64_e32 v[8:9], v[96:97]
	v_mov_b64_e32 v[12:13], v[96:97]
	v_mov_b64_e32 v[24:25], v[96:97]
	v_mov_b64_e32 v[28:29], v[96:97]
	v_mov_b64_e32 v[40:41], v[96:97]
	v_mov_b64_e32 v[44:45], v[96:97]
	v_mov_b64_e32 v[56:57], v[96:97]
	v_mov_b64_e32 v[60:61], v[96:97]
	s_addc_u32 s10, s43, 0
	s_mov_b32 s6, -2
	s_mov_b64 s[60:61], 0
	v_mov_b64_e32 v[2:3], v[98:99]
	v_mov_b64_e32 v[6:7], v[98:99]
	v_mov_b64_e32 v[18:19], v[98:99]
	v_mov_b64_e32 v[22:23], v[98:99]
	v_mov_b64_e32 v[34:35], v[98:99]
	v_mov_b64_e32 v[38:39], v[98:99]
	v_mov_b64_e32 v[50:51], v[98:99]
	v_mov_b64_e32 v[54:55], v[98:99]
	v_mov_b64_e32 v[10:11], v[98:99]
	v_mov_b64_e32 v[14:15], v[98:99]
	v_mov_b64_e32 v[26:27], v[98:99]
	v_mov_b64_e32 v[30:31], v[98:99]
	v_mov_b64_e32 v[42:43], v[98:99]
	v_mov_b64_e32 v[46:47], v[98:99]
	v_mov_b64_e32 v[58:59], v[98:99]
	v_mov_b64_e32 v[62:63], v[98:99]
	v_mov_b32_e32 v65, v64
	v_mov_b32_e32 v66, v64
	v_mov_b32_e32 v67, v64
	v_mov_b32_e32 v68, v64
	v_mov_b32_e32 v69, v64
	v_mov_b32_e32 v70, v64
	v_mov_b32_e32 v71, v64
	v_mov_b32_e32 v80, v64
	v_mov_b32_e32 v81, v64
	v_mov_b32_e32 v82, v64
	v_mov_b32_e32 v83, v64
	v_mov_b32_e32 v84, v64
	v_mov_b32_e32 v85, v64
	v_mov_b32_e32 v86, v64
	v_mov_b32_e32 v87, v64
	v_mov_b32_e32 v98, v64
	v_mov_b32_e32 v99, v64
	v_mov_b32_e32 v100, v64
	v_mov_b32_e32 v101, v64
	v_mov_b32_e32 v106, v64
	v_mov_b32_e32 v107, v64
	v_mov_b32_e32 v108, v64
	v_mov_b32_e32 v109, v64
	v_mov_b32_e32 v126, v64
	v_mov_b32_e32 v127, v64
	v_mov_b32_e32 v128, v64
	v_mov_b32_e32 v129, v64
	v_mov_b32_e32 v130, v64
	v_mov_b32_e32 v131, v64
	v_mov_b32_e32 v132, v64
	v_mov_b32_e32 v133, v64
	v_mov_b32_e32 v72, v64
	v_mov_b32_e32 v73, v64
	v_mov_b32_e32 v74, v64
	v_mov_b32_e32 v75, v64
	v_mov_b32_e32 v76, v64
	v_mov_b32_e32 v77, v64
	v_mov_b32_e32 v78, v64
	v_mov_b32_e32 v79, v64
	v_mov_b32_e32 v88, v64
	v_mov_b32_e32 v89, v64
	v_mov_b32_e32 v90, v64
	v_mov_b32_e32 v91, v64
	v_mov_b32_e32 v92, v64
	v_mov_b32_e32 v93, v64
	v_mov_b32_e32 v94, v64
	v_mov_b32_e32 v95, v64
	v_mov_b32_e32 v114, v64
	v_mov_b32_e32 v115, v64
	v_mov_b32_e32 v116, v64
	v_mov_b32_e32 v117, v64
	v_mov_b32_e32 v118, v64
	v_mov_b32_e32 v119, v64
	v_mov_b32_e32 v120, v64
	v_mov_b32_e32 v121, v64
	v_mov_b32_e32 v150, v64
	v_mov_b32_e32 v151, v64
	v_mov_b32_e32 v152, v64
	v_mov_b32_e32 v153, v64
	v_mov_b32_e32 v154, v64
	v_mov_b32_e32 v155, v64
	v_mov_b32_e32 v156, v64
	v_mov_b32_e32 v157, v64
	v_add_u32_e32 v250, 0x10000, v222
	v_add_u32_e32 v251, 0x14000, v222
	v_add_u32_e32 v252, 0x18000, v222
	v_add_u32_e32 v253, 0x1c000, v222
	s_cmp_eq_u32 s38, 1
	s_cbranch_scc1 .Lrebar_1
	s_andn2_b64 vcc, exec, s[14:15]
	s_cbranch_vccnz .Lrebar_1
	s_barrier
.Lrebar_1:
	s_branch .LBB0_689

.LBB0_697:
	s_and_b64 vcc, exec, s[40:41]
	s_mov_b64 s[40:41], -1
	s_cbranch_vccnz .LBB0_675
	s_andn2_b64 vcc, exec, s[14:15]
	s_cbranch_vccnz .LBB0_674
	s_branch .LBB0_674

.LBB0_727:
	s_cmp_eq_u32 s77, 2
	s_cselect_b32 s4, 0x4c0000, 0
	s_cmp_eq_u32 s78, 2
	s_cselect_b64 s[58:59], -1, 0
	s_ashr_i32 s45, s44, 31
	s_lshl_b64 s[6:7], s[44:45], 20
	s_add_u32 s48, s34, s6
	s_addc_u32 s49, s35, s7
	s_and_b64 s[6:7], s[56:57], exec
	s_cselect_b32 s45, s49, s43
	s_cselect_b32 s80, s48, s42
	s_add_u32 s6, s54, 0x80
	s_addc_u32 s7, s55, 0
	v_lshl_add_u64 v[0:1], s[6:7], 0, v[206:207]
	v_lshl_add_u64 v[210:211], v[0:1], 0, s[52:53]
	v_lshl_add_u64 v[0:1], s[6:7], 0, v[208:209]
	v_mov_b32_e32 v97, v96
	v_lshl_add_u64 v[212:213], v[0:1], 0, s[52:53]
	s_add_u32 s81, s42, 0x100
	v_mov_b32_e32 v98, v96
	v_mov_b32_e32 v99, v96
	v_mov_b32_e32 v64, 0
	v_mov_b64_e32 v[0:1], v[96:97]
	v_mov_b64_e32 v[4:5], v[96:97]
	v_mov_b64_e32 v[16:17], v[96:97]
	v_mov_b64_e32 v[20:21], v[96:97]
	v_mov_b64_e32 v[32:33], v[96:97]
	v_mov_b64_e32 v[36:37], v[96:97]
	v_mov_b64_e32 v[48:49], v[96:97]
	v_mov_b64_e32 v[52:53], v[96:97]
	v_mov_b64_e32 v[8:9], v[96:97]
	v_mov_b64_e32 v[12:13], v[96:97]
	v_mov_b64_e32 v[24:25], v[96:97]
	v_mov_b64_e32 v[28:29], v[96:97]
	v_mov_b64_e32 v[40:41], v[96:97]
	v_mov_b64_e32 v[44:45], v[96:97]
	v_mov_b64_e32 v[56:57], v[96:97]
	v_mov_b64_e32 v[60:61], v[96:97]
	s_addc_u32 s10, s43, 0
	s_mov_b32 s6, -2
	s_mov_b64 s[60:61], 0
	v_mov_b64_e32 v[2:3], v[98:99]
	v_mov_b64_e32 v[6:7], v[98:99]
	v_mov_b64_e32 v[18:19], v[98:99]
	v_mov_b64_e32 v[22:23], v[98:99]
	v_mov_b64_e32 v[34:35], v[98:99]
	v_mov_b64_e32 v[38:39], v[98:99]
	v_mov_b64_e32 v[50:51], v[98:99]
	v_mov_b64_e32 v[54:55], v[98:99]
	v_mov_b64_e32 v[10:11], v[98:99]
	v_mov_b64_e32 v[14:15], v[98:99]
	v_mov_b64_e32 v[26:27], v[98:99]
	v_mov_b64_e32 v[30:31], v[98:99]
	v_mov_b64_e32 v[42:43], v[98:99]
	v_mov_b64_e32 v[46:47], v[98:99]
	v_mov_b64_e32 v[58:59], v[98:99]
	v_mov_b64_e32 v[62:63], v[98:99]
	v_mov_b32_e32 v65, v64
	v_mov_b32_e32 v66, v64
	v_mov_b32_e32 v67, v64
	v_mov_b32_e32 v68, v64
	v_mov_b32_e32 v69, v64
	v_mov_b32_e32 v70, v64
	v_mov_b32_e32 v71, v64
	v_mov_b32_e32 v80, v64
	v_mov_b32_e32 v81, v64
	v_mov_b32_e32 v82, v64
	v_mov_b32_e32 v83, v64
	v_mov_b32_e32 v84, v64
	v_mov_b32_e32 v85, v64
	v_mov_b32_e32 v86, v64
	v_mov_b32_e32 v87, v64
	v_mov_b32_e32 v98, v64
	v_mov_b32_e32 v99, v64
	v_mov_b32_e32 v100, v64
	v_mov_b32_e32 v101, v64
	v_mov_b32_e32 v102, v64
	v_mov_b32_e32 v103, v64
	v_mov_b32_e32 v104, v64
	v_mov_b32_e32 v105, v64
	v_mov_b32_e32 v114, v64
	v_mov_b32_e32 v115, v64
	v_mov_b32_e32 v116, v64
	v_mov_b32_e32 v117, v64
	v_mov_b32_e32 v118, v64
	v_mov_b32_e32 v119, v64
	v_mov_b32_e32 v120, v64
	v_mov_b32_e32 v121, v64
	v_mov_b32_e32 v72, v64
	v_mov_b32_e32 v73, v64
	v_mov_b32_e32 v74, v64
	v_mov_b32_e32 v75, v64
	v_mov_b32_e32 v76, v64
	v_mov_b32_e32 v77, v64
	v_mov_b32_e32 v78, v64
	v_mov_b32_e32 v79, v64
	v_mov_b32_e32 v88, v64
	v_mov_b32_e32 v89, v64
	v_mov_b32_e32 v90, v64
	v_mov_b32_e32 v91, v64
	v_mov_b32_e32 v92, v64
	v_mov_b32_e32 v93, v64
	v_mov_b32_e32 v94, v64
	v_mov_b32_e32 v95, v64
	v_mov_b32_e32 v106, v64
	v_mov_b32_e32 v107, v64
	v_mov_b32_e32 v108, v64
	v_mov_b32_e32 v109, v64
	v_mov_b32_e32 v110, v64
	v_mov_b32_e32 v111, v64
	v_mov_b32_e32 v112, v64
	v_mov_b32_e32 v113, v64
	v_mov_b32_e32 v130, v64
	v_mov_b32_e32 v131, v64
	v_mov_b32_e32 v132, v64
	v_mov_b32_e32 v133, v64
	v_mov_b32_e32 v134, v64
	v_mov_b32_e32 v135, v64
	v_mov_b32_e32 v136, v64
	v_mov_b32_e32 v137, v64
	v_add_u32_e32 v250, 0x10000, v222
	v_add_u32_e32 v251, 0x14000, v222
	v_add_u32_e32 v252, 0x18000, v222
	v_add_u32_e32 v253, 0x1c000, v222
	s_cmp_eq_u32 s75, 1
	s_cbranch_scc1 .Lrebar_2
	s_andn2_b64 vcc, exec, s[14:15]
	s_cbranch_vccnz .Lrebar_2
	s_barrier

.LBB0_767:
	s_cmp_eq_u32 s77, 2
	s_cselect_b32 s4, 0x4c0000, 0
	s_cmp_eq_u32 s78, 2
	s_cselect_b64 s[56:57], -1, 0
	s_ashr_i32 s19, s18, 31
	s_lshl_b64 s[6:7], s[18:19], 20
	s_add_u32 s46, s38, s6
	s_addc_u32 s47, s39, s7
	s_and_b64 s[6:7], s[54:55], exec
	s_cselect_b32 s19, s47, s43
	s_cselect_b32 s80, s46, s42
	s_add_u32 s6, s52, 0x80
	s_addc_u32 s7, s53, 0
	v_lshl_add_u64 v[0:1], s[6:7], 0, v[206:207]
	v_lshl_add_u64 v[210:211], v[0:1], 0, s[50:51]
	v_lshl_add_u64 v[0:1], s[6:7], 0, v[208:209]
	v_mov_b32_e32 v97, v96
	v_lshl_add_u64 v[212:213], v[0:1], 0, s[50:51]
	s_add_u32 s81, s42, 0x100
	v_mov_b32_e32 v98, v96
	v_mov_b32_e32 v99, v96
	v_mov_b32_e32 v64, 0
	v_mov_b64_e32 v[0:1], v[96:97]
	v_mov_b64_e32 v[4:5], v[96:97]
	v_mov_b64_e32 v[16:17], v[96:97]
	v_mov_b64_e32 v[20:21], v[96:97]
	v_mov_b64_e32 v[32:33], v[96:97]
	v_mov_b64_e32 v[36:37], v[96:97]
	v_mov_b64_e32 v[48:49], v[96:97]
	v_mov_b64_e32 v[52:53], v[96:97]
	v_mov_b64_e32 v[8:9], v[96:97]
	v_mov_b64_e32 v[12:13], v[96:97]
	v_mov_b64_e32 v[24:25], v[96:97]
	v_mov_b64_e32 v[28:29], v[96:97]
	v_mov_b64_e32 v[40:41], v[96:97]
	v_mov_b64_e32 v[44:45], v[96:97]
	v_mov_b64_e32 v[56:57], v[96:97]
	v_mov_b64_e32 v[60:61], v[96:97]
	s_addc_u32 s6, s43, 0
	s_mov_b32 s7, -2
	s_mov_b64 s[58:59], 0
	v_mov_b64_e32 v[2:3], v[98:99]
	v_mov_b64_e32 v[6:7], v[98:99]
	v_mov_b64_e32 v[18:19], v[98:99]
	v_mov_b64_e32 v[22:23], v[98:99]
	v_mov_b64_e32 v[34:35], v[98:99]
	v_mov_b64_e32 v[38:39], v[98:99]
	v_mov_b64_e32 v[50:51], v[98:99]
	v_mov_b64_e32 v[54:55], v[98:99]
	v_mov_b64_e32 v[10:11], v[98:99]
	v_mov_b64_e32 v[14:15], v[98:99]
	v_mov_b64_e32 v[26:27], v[98:99]
	v_mov_b64_e32 v[30:31], v[98:99]
	v_mov_b64_e32 v[42:43], v[98:99]
	v_mov_b64_e32 v[46:47], v[98:99]
	v_mov_b64_e32 v[58:59], v[98:99]
	v_mov_b64_e32 v[62:63], v[98:99]
	v_mov_b32_e32 v65, v64
	v_mov_b32_e32 v66, v64
	v_mov_b32_e32 v67, v64
	v_mov_b32_e32 v68, v64
	v_mov_b32_e32 v69, v64
	v_mov_b32_e32 v70, v64
	v_mov_b32_e32 v71, v64
	v_mov_b32_e32 v80, v64
	v_mov_b32_e32 v81, v64
	v_mov_b32_e32 v82, v64
	v_mov_b32_e32 v83, v64
	v_mov_b32_e32 v84, v64
	v_mov_b32_e32 v85, v64
	v_mov_b32_e32 v86, v64
	v_mov_b32_e32 v87, v64
	v_mov_b32_e32 v98, v64
	v_mov_b32_e32 v99, v64
	v_mov_b32_e32 v100, v64
	v_mov_b32_e32 v101, v64
	v_mov_b32_e32 v102, v64
	v_mov_b32_e32 v103, v64
	v_mov_b32_e32 v104, v64
	v_mov_b32_e32 v105, v64
	v_mov_b32_e32 v114, v64
	v_mov_b32_e32 v115, v64
	v_mov_b32_e32 v116, v64
	v_mov_b32_e32 v117, v64
	v_mov_b32_e32 v118, v64
	v_mov_b32_e32 v119, v64
	v_mov_b32_e32 v120, v64
	v_mov_b32_e32 v121, v64
	v_mov_b32_e32 v72, v64
	v_mov_b32_e32 v73, v64
	v_mov_b32_e32 v74, v64
	v_mov_b32_e32 v75, v64
	v_mov_b32_e32 v76, v64
	v_mov_b32_e32 v77, v64
	v_mov_b32_e32 v78, v64
	v_mov_b32_e32 v79, v64
	v_mov_b32_e32 v88, v64
	v_mov_b32_e32 v89, v64
	v_mov_b32_e32 v90, v64
	v_mov_b32_e32 v91, v64
	v_mov_b32_e32 v92, v64
	v_mov_b32_e32 v93, v64
	v_mov_b32_e32 v94, v64
	v_mov_b32_e32 v95, v64
	v_mov_b32_e32 v106, v64
	v_mov_b32_e32 v107, v64
	v_mov_b32_e32 v108, v64
	v_mov_b32_e32 v109, v64
	v_mov_b32_e32 v110, v64
	v_mov_b32_e32 v111, v64
	v_mov_b32_e32 v112, v64
	v_mov_b32_e32 v113, v64
	v_mov_b32_e32 v130, v64
	v_mov_b32_e32 v131, v64
	v_mov_b32_e32 v132, v64
	v_mov_b32_e32 v133, v64
	v_mov_b32_e32 v134, v64
	v_mov_b32_e32 v135, v64
	v_mov_b32_e32 v136, v64
	v_mov_b32_e32 v137, v64
	v_add_u32_e32 v250, 0x14000, v222
	v_add_u32_e32 v251, 0x18000, v222
	v_add_u32_e32 v252, 0x1c000, v222
	s_cmp_eq_u32 s75, 1
	s_cbranch_scc1 .Lrebar_3
	s_andn2_b64 vcc, exec, s[12:13]
	s_cbranch_vccnz .Lrebar_3
	s_barrier

.LBB0_777:
	s_and_b64 vcc, exec, s[40:41]
	s_mov_b64 s[40:41], -1
	s_cbranch_vccnz .LBB0_755
	s_andn2_b64 vcc, exec, s[12:13]
	s_cbranch_vccnz .LBB0_754
	s_branch .LBB0_754

.LBB0_873:
	s_ashr_i32 s43, s42, 31
	s_lshl_b64 s[14:15], s[42:43], 19
	s_add_u32 s46, s68, s14
	s_addc_u32 s47, s69, s15
	s_and_b64 s[14:15], s[44:45], exec
	s_cselect_b32 s17, s47, s57
	s_cselect_b32 s43, s46, s56
	s_cmp_eq_u32 s16, 2
	s_cselect_b32 s4, 0x80000, 0
	s_cmp_eq_u32 s81, 2
	s_cselect_b64 s[58:59], -1, 0
	s_ashr_i32 s41, s40, 31
	s_lshl_b64 s[14:15], s[40:41], 20
	s_add_u32 s48, s70, s14
	s_addc_u32 s49, s71, s15
	s_and_b64 s[14:15], s[44:45], exec
	s_cselect_b32 s41, s49, s39
	s_cselect_b32 s14, s48, s38
	s_add_u32 s26, s56, 0x80
	s_addc_u32 s27, s57, 0
	v_lshl_add_u64 v[0:1], s[26:27], 0, v[222:223]
	v_lshl_add_u64 v[226:227], v[0:1], 0, s[54:55]
	v_lshl_add_u64 v[0:1], s[26:27], 0, v[224:225]
	v_mov_b32_e32 v97, v96
	v_lshl_add_u64 v[228:229], v[0:1], 0, s[54:55]
	s_add_u32 s15, s38, 0x100
	v_mov_b32_e32 v98, v96
	v_mov_b32_e32 v99, v96
	v_mov_b32_e32 v52, 0
	v_mov_b64_e32 v[0:1], v[96:97]
	v_mov_b64_e32 v[4:5], v[96:97]
	v_mov_b64_e32 v[8:9], v[96:97]
	v_mov_b64_e32 v[12:13], v[96:97]
	v_mov_b64_e32 v[16:17], v[96:97]
	v_mov_b64_e32 v[20:21], v[96:97]
	v_mov_b64_e32 v[24:25], v[96:97]
	v_mov_b64_e32 v[28:29], v[96:97]
	v_mov_b64_e32 v[32:33], v[96:97]
	v_mov_b64_e32 v[36:37], v[96:97]
	v_mov_b64_e32 v[40:41], v[96:97]
	v_mov_b64_e32 v[44:45], v[96:97]
	v_mov_b64_e32 v[48:49], v[96:97]
	v_mov_b64_e32 v[56:57], v[96:97]
	v_mov_b64_e32 v[60:61], v[96:97]
	v_mov_b64_e32 v[68:69], v[96:97]
	s_mov_b32 s0, s89
	s_addc_u32 s26, s39, 0
	s_mov_b32 s27, -2
	s_mov_b64 s[60:61], 0
	v_mov_b64_e32 v[2:3], v[98:99]
	v_mov_b64_e32 v[6:7], v[98:99]
	v_mov_b64_e32 v[10:11], v[98:99]
	v_mov_b64_e32 v[14:15], v[98:99]
	v_mov_b64_e32 v[18:19], v[98:99]
	v_mov_b64_e32 v[22:23], v[98:99]
	v_mov_b64_e32 v[26:27], v[98:99]
	v_mov_b64_e32 v[30:31], v[98:99]
	v_mov_b64_e32 v[34:35], v[98:99]
	v_mov_b64_e32 v[38:39], v[98:99]
	v_mov_b64_e32 v[42:43], v[98:99]
	v_mov_b64_e32 v[46:47], v[98:99]
	v_mov_b64_e32 v[50:51], v[98:99]
	v_mov_b64_e32 v[58:59], v[98:99]
	v_mov_b64_e32 v[62:63], v[98:99]
	v_mov_b64_e32 v[70:71], v[98:99]
	v_mov_b32_e32 v53, v52
	v_mov_b32_e32 v54, v52
	v_mov_b32_e32 v55, v52
	v_mov_b32_e32 v64, v52
	v_mov_b32_e32 v65, v52
	v_mov_b32_e32 v66, v52
	v_mov_b32_e32 v67, v52
	v_mov_b32_e32 v72, v52
	v_mov_b32_e32 v73, v52
	v_mov_b32_e32 v74, v52
	v_mov_b32_e32 v75, v52
	v_mov_b32_e32 v76, v52
	v_mov_b32_e32 v77, v52
	v_mov_b32_e32 v78, v52
	v_mov_b32_e32 v79, v52
	v_mov_b32_e32 v80, v52
	v_mov_b32_e32 v81, v52
	v_mov_b32_e32 v82, v52
	v_mov_b32_e32 v83, v52
	v_mov_b32_e32 v84, v52
	v_mov_b32_e32 v85, v52
	v_mov_b32_e32 v86, v52
	v_mov_b32_e32 v87, v52
	v_mov_b32_e32 v88, v52
	v_mov_b32_e32 v89, v52
	v_mov_b32_e32 v90, v52
	v_mov_b32_e32 v91, v52
	v_mov_b32_e32 v92, v52
	v_mov_b32_e32 v93, v52
	v_mov_b32_e32 v94, v52
	v_mov_b32_e32 v95, v52
	v_mov_b32_e32 v98, v52
	v_mov_b32_e32 v99, v52
	v_mov_b32_e32 v100, v52
	v_mov_b32_e32 v101, v52
	v_mov_b32_e32 v102, v52
	v_mov_b32_e32 v103, v52
	v_mov_b32_e32 v104, v52
	v_mov_b32_e32 v105, v52
	v_mov_b32_e32 v106, v52
	v_mov_b32_e32 v107, v52
	v_mov_b32_e32 v108, v52
	v_mov_b32_e32 v109, v52
	v_mov_b32_e32 v110, v52
	v_mov_b32_e32 v111, v52
	v_mov_b32_e32 v112, v52
	v_mov_b32_e32 v113, v52
	v_mov_b32_e32 v114, v52
	v_mov_b32_e32 v115, v52
	v_mov_b32_e32 v116, v52
	v_mov_b32_e32 v117, v52
	v_mov_b32_e32 v118, v52
	v_mov_b32_e32 v119, v52
	v_mov_b32_e32 v120, v52
	v_mov_b32_e32 v121, v52
	v_mov_b32_e32 v122, v52
	v_mov_b32_e32 v123, v52
	v_mov_b32_e32 v124, v52
	v_mov_b32_e32 v125, v52
	v_mov_b32_e32 v126, v52
	v_mov_b32_e32 v127, v52
	v_mov_b32_e32 v128, v52
	v_mov_b32_e32 v129, v52
	s_cmp_eq_u32 s80, 1
	s_cbranch_scc1 .Lrebar_4
	v_readlane_b32 s100, v255, 44
	v_readlane_b32 s101, v255, 45
	s_andn2_b64 vcc, exec, s[100:101]
	s_cbranch_vccnz .Lrebar_4
	s_barrier

.LBB0_885:
	s_andn2_b64 vcc, exec, s[44:45]
	s_mov_b64 s[38:39], -1
	s_cbranch_vccnz .LBB0_863
	v_readlane_b32 s0, v255, 44
	v_readlane_b32 s1, v255, 45
	s_andn2_b64 vcc, exec, s[0:1]
	s_cbranch_vccnz .LBB0_862
	s_branch .LBB0_862

.LBB0_1053:
	s_ashr_i32 s45, s44, 31
	s_lshl_b64 s[26:27], s[44:45], 19
	s_add_u32 s48, s37, s26
	s_addc_u32 s49, s62, s27
	s_and_b64 s[26:27], s[46:47], exec
	s_cselect_b32 s9, s49, s41
	s_cselect_b32 s45, s48, s40
	s_cmp_eq_u32 s75, 2
	s_cselect_b32 s4, 0x80000, 0
	s_cmp_eq_u32 s65, 2
	s_cselect_b64 s[52:53], -1, 0
	s_ashr_i32 s43, s42, 31
	s_lshl_b64 s[26:27], s[42:43], 20
	s_add_u32 s50, s63, s26
	s_addc_u32 s51, s64, s27
	s_and_b64 s[26:27], s[46:47], exec
	s_cselect_b32 s43, s51, s39
	s_cselect_b32 s76, s50, s38
	s_add_u32 s26, s40, 0x80
	s_addc_u32 s27, s41, 0
	v_lshl_add_u64 v[0:1], s[26:27], 0, v[202:203]
	v_lshl_add_u64 v[206:207], v[0:1], 0, s[10:11]
	v_lshl_add_u64 v[0:1], s[26:27], 0, v[204:205]
	v_mov_b32_e32 v97, v96
	v_lshl_add_u64 v[208:209], v[0:1], 0, s[10:11]
	s_add_u32 s77, s38, 0x100
	v_mov_b32_e32 v98, v96
	v_mov_b32_e32 v99, v96
	v_mov_b32_e32 v64, 0
	v_mov_b64_e32 v[0:1], v[96:97]
	v_mov_b64_e32 v[4:5], v[96:97]
	v_mov_b64_e32 v[16:17], v[96:97]
	v_mov_b64_e32 v[20:21], v[96:97]
	v_mov_b64_e32 v[32:33], v[96:97]
	v_mov_b64_e32 v[36:37], v[96:97]
	v_mov_b64_e32 v[48:49], v[96:97]
	v_mov_b64_e32 v[52:53], v[96:97]
	v_mov_b64_e32 v[8:9], v[96:97]
	v_mov_b64_e32 v[12:13], v[96:97]
	v_mov_b64_e32 v[24:25], v[96:97]
	v_mov_b64_e32 v[28:29], v[96:97]
	v_mov_b64_e32 v[40:41], v[96:97]
	v_mov_b64_e32 v[44:45], v[96:97]
	v_mov_b64_e32 v[56:57], v[96:97]
	v_mov_b64_e32 v[60:61], v[96:97]
	s_addc_u32 s26, s39, 0
	s_mov_b32 s27, -2
	s_mov_b64 s[54:55], 0
	v_mov_b64_e32 v[2:3], v[98:99]
	v_mov_b64_e32 v[6:7], v[98:99]
	v_mov_b64_e32 v[18:19], v[98:99]
	v_mov_b64_e32 v[22:23], v[98:99]
	v_mov_b64_e32 v[34:35], v[98:99]
	v_mov_b64_e32 v[38:39], v[98:99]
	v_mov_b64_e32 v[50:51], v[98:99]
	v_mov_b64_e32 v[54:55], v[98:99]
	v_mov_b64_e32 v[10:11], v[98:99]
	v_mov_b64_e32 v[14:15], v[98:99]
	v_mov_b64_e32 v[26:27], v[98:99]
	v_mov_b64_e32 v[30:31], v[98:99]
	v_mov_b64_e32 v[42:43], v[98:99]
	v_mov_b64_e32 v[46:47], v[98:99]
	v_mov_b64_e32 v[58:59], v[98:99]
	v_mov_b64_e32 v[62:63], v[98:99]
	v_mov_b32_e32 v65, v64
	v_mov_b32_e32 v66, v64
	v_mov_b32_e32 v67, v64
	v_mov_b32_e32 v68, v64
	v_mov_b32_e32 v69, v64
	v_mov_b32_e32 v70, v64
	v_mov_b32_e32 v71, v64
	v_mov_b32_e32 v72, v64
	v_mov_b32_e32 v73, v64
	v_mov_b32_e32 v74, v64
	v_mov_b32_e32 v75, v64
	v_mov_b32_e32 v76, v64
	v_mov_b32_e32 v77, v64
	v_mov_b32_e32 v78, v64
	v_mov_b32_e32 v79, v64
	v_mov_b32_e32 v84, v64
	v_mov_b32_e32 v85, v64
	v_mov_b32_e32 v86, v64
	v_mov_b32_e32 v87, v64
	v_mov_b32_e32 v92, v64
	v_mov_b32_e32 v93, v64
	v_mov_b32_e32 v94, v64
	v_mov_b32_e32 v95, v64
	v_mov_b32_e32 v102, v64
	v_mov_b32_e32 v103, v64
	v_mov_b32_e32 v104, v64
	v_mov_b32_e32 v105, v64
	v_mov_b32_e32 v110, v64
	v_mov_b32_e32 v111, v64
	v_mov_b32_e32 v112, v64
	v_mov_b32_e32 v113, v64
	v_mov_b32_e32 v80, v64
	v_mov_b32_e32 v81, v64
	v_mov_b32_e32 v82, v64
	v_mov_b32_e32 v83, v64
	v_mov_b32_e32 v88, v64
	v_mov_b32_e32 v89, v64
	v_mov_b32_e32 v90, v64
	v_mov_b32_e32 v91, v64
	v_mov_b32_e32 v98, v64
	v_mov_b32_e32 v99, v64
	v_mov_b32_e32 v100, v64
	v_mov_b32_e32 v101, v64
	v_mov_b32_e32 v106, v64
	v_mov_b32_e32 v107, v64
	v_mov_b32_e32 v108, v64
	v_mov_b32_e32 v109, v64
	v_mov_b32_e32 v114, v64
	v_mov_b32_e32 v115, v64
	v_mov_b32_e32 v116, v64
	v_mov_b32_e32 v117, v64
	v_mov_b32_e32 v118, v64
	v_mov_b32_e32 v119, v64
	v_mov_b32_e32 v120, v64
	v_mov_b32_e32 v121, v64
	v_mov_b32_e32 v122, v64
	v_mov_b32_e32 v123, v64
	v_mov_b32_e32 v124, v64
	v_mov_b32_e32 v125, v64
	v_mov_b32_e32 v126, v64
	v_mov_b32_e32 v127, v64
	v_mov_b32_e32 v128, v64
	v_mov_b32_e32 v129, v64
	v_add_u32_e32 v224, 0x10000, v218
	v_add_u32_e32 v225, 0x14000, v218
	v_add_u32_e32 v226, 0x18000, v218
	v_add_u32_e32 v227, 0x1c000, v218
	s_cmp_eq_u32 s74, 1
	s_cbranch_scc1 .Lrebar_5
	s_andn2_b64 vcc, exec, s[14:15]
	s_cbranch_vccnz .Lrebar_5
	s_barrier

.LBB0_1063:
	s_andn2_b64 vcc, exec, s[46:47]
	s_mov_b64 s[8:9], -1
	s_cbranch_vccnz .LBB0_1043
	s_andn2_b64 vcc, exec, s[14:15]
	s_cbranch_vccnz .LBB0_1042
	s_branch .LBB0_1042
